# attention: K/V fragment LDS reads of the next key block issued behind the previous block's MFMAs (fresh registers), first PV group reads hoisted into the exp section
# speedup vs baseline: 1.0097x; 1.0045x over previous
.Lrm_done_c:
	s_ashr_i32 s2, s98, 8
	s_mul_hi_i32 s3, s2, 0x55555556
	s_lshr_b32 s35, s3, 31
	s_add_i32 s60, s3, s35
	s_mul_i32 s3, s60, 3
	s_and_b32 s61, s98, 31
	s_sub_i32 s68, s2, s3
	s_cmp_eq_u32 s68, 1
	s_waitcnt lgkmcnt(1)
	v_mfma_f32_16x16x32_bf16 v[48:51], v[48:51], v[44:47], 0
	s_cselect_b32 s2, 2, 4
	s_cmp_lg_u32 s68, 0
	s_cselect_b32 s36, s2, 0
	s_lshr_b32 s35, s61, s36
	s_cmp_eq_u32 s35, 0
	s_waitcnt lgkmcnt(0)
	v_mfma_f32_16x16x32_bf16 v[48:51], v[52:55], v[40:43], v[48:51]
	ds_read_b128 v[182:185], v98
	ds_read_b128 v[186:189], v98 offset:64
	s_cselect_b64 s[2:3], -1, 0
	s_and_b64 s[76:77], s[8:9], s[2:3]
	s_nor_b64 s[82:83], s[6:7], s[76:77]
	v_mov_b32_e32 v59, 0xff800000
	v_mov_b32_e32 v110, 0xff800000
	v_mov_b32_e32 v107, 0xff800000
	v_mov_b32_e32 v52, 0xff800000
	v_mov_b32_e32 v53, 0xff800000
	v_mov_b32_e32 v61, 0xff800000
	s_and_saveexec_b64 s[76:77], s[82:83]
	s_cbranch_execz .LBB0_858
	v_readlane_b32 s42, v255, 32
	v_mul_f32_e32 v107, 0x3e000000, v48
	v_readlane_b32 s43, v255, 33
	s_and_saveexec_b64 s[82:83], s[42:43]
	s_xor_b64 s[82:83], exec, s[82:83]
	s_cbranch_execz .LBB0_855
	v_readlane_b32 s42, v255, 34
	v_readlane_b32 s43, v255, 35
	s_and_saveexec_b64 s[90:91], s[42:43]
	s_xor_b64 s[90:91], exec, s[90:91]
	v_mov_b32_e32 v48, v49
	v_mov_b32_e32 v49, v50
	s_mov_b32 s42, 0x3e000000
	v_pk_mul_f32 v[52:53], v[48:49], s[42:43] op_sel_hi:[1,0]
	s_mov_b32 s42, 0xff800000
	v_max3_f32 v48, v107, s42, v52
	v_mul_f32_e32 v61, 0x3e000000, v51
	v_max3_f32 v110, v48, v53, v61
	s_andn2_saveexec_b64 s[90:91], s[90:91]
	s_cbranch_execz .LBB0_854
	v_mul_f32_e32 v48, 0x3e000000, v49
	v_mul_f32_e32 v49, 0x3e000000, v50
	v_cndmask_b32_e64 v107, v107, v151, s[14:15]
	v_cndmask_b32_e64 v52, v151, v48, s[16:17]
	s_mov_b32 s42, 0xff800000
	v_cndmask_b32_e64 v53, v49, v151, s[18:19]
	v_mul_f32_e32 v49, 0x3e000000, v51
	v_max3_f32 v48, v107, s42, v52
	v_cndmask_b32_e64 v61, v49, v151, s[20:21]
	v_max3_f32 v110, v48, v53, v61

.LBB0_858:
	s_or_b64 exec, exec, s[76:77]
	s_and_b64 s[76:77], s[30:31], s[2:3]
	s_nor_b64 s[76:77], s[28:29], s[76:77]
	v_mov_b32_e32 v54, 0xff800000
	s_waitcnt lgkmcnt(1)
	v_mfma_f32_16x16x32_bf16 v[48:51], v[182:185], v[44:47], 0
	v_mov_b32_e32 v55, 0xff800000
	v_mov_b32_e32 v108, 0xff800000
	s_waitcnt lgkmcnt(0)
	v_mfma_f32_16x16x32_bf16 v[48:51], v[186:189], v[40:43], v[48:51]
	ds_read_b128 v[190:193], v99
	ds_read_b128 v[194:197], v99 offset:64
	s_and_saveexec_b64 vcc, s[76:77]
	s_cbranch_execz .LBB0_868
	v_readlane_b32 s42, v255, 36
	s_nop 4
	v_mul_f32_e32 v59, 0x3e000000, v48
	v_readlane_b32 s43, v255, 37
	s_and_saveexec_b64 s[76:77], s[42:43]
	s_xor_b64 s[76:77], exec, s[76:77]
	s_cbranch_execz .LBB0_865
	v_readlane_b32 s42, v255, 38
	v_readlane_b32 s43, v255, 39
	s_and_saveexec_b64 s[82:83], s[42:43]
	s_xor_b64 s[82:83], exec, s[82:83]
	v_mov_b32_e32 v48, v49
	v_mov_b32_e32 v49, v50
	s_mov_b32 s42, 0x3e000000
	v_pk_mul_f32 v[54:55], v[48:49], s[42:43] op_sel_hi:[1,0]
	v_mul_f32_e32 v108, 0x3e000000, v51
	v_max3_f32 v48, v110, v59, v54
	v_max3_f32 v110, v48, v55, v108
	s_andn2_saveexec_b64 s[82:83], s[82:83]
	v_mul_f32_e32 v48, 0x3e000000, v49
	v_mul_f32_e32 v49, 0x3e000000, v50
	v_cndmask_b32_e64 v59, v59, v151, s[14:15]
	v_cndmask_b32_e64 v54, v151, v48, s[16:17]
	v_cndmask_b32_e64 v55, v49, v151, s[18:19]
	v_mul_f32_e32 v49, 0x3e000000, v51
	v_max3_f32 v48, v110, v59, v54
	v_cndmask_b32_e64 v108, v49, v151, s[20:21]
	v_max3_f32 v110, v48, v55, v108
	s_or_b64 exec, exec, s[82:83]

.LBB0_868:
	s_or_b64 exec, exec, vcc
	s_nop 4
	s_and_b64 s[76:77], s[40:41], s[2:3]
	s_nor_b64 s[76:77], s[38:39], s[76:77]
	v_mov_b32_e32 v109, 0xff800000
	s_waitcnt lgkmcnt(1)
	v_mfma_f32_16x16x32_bf16 v[48:51], v[190:193], v[44:47], 0
	v_mov_b32_e32 v111, 0xff800000
	v_mov_b32_e32 v112, 0xff800000
	s_waitcnt lgkmcnt(0)
	v_mfma_f32_16x16x32_bf16 v[48:51], v[194:197], v[40:43], v[48:51]
	ds_read_b128 v[182:185], v100
	ds_read_b128 v[186:189], v100 offset:64
	v_mov_b32_e32 v62, 0xff800000
	v_mov_b32_e32 v63, 0xff800000
	s_and_saveexec_b64 vcc, s[76:77]
	s_cbranch_execz .LBB0_878
	v_readlane_b32 s42, v255, 40
	s_nop 2
	v_mul_f32_e32 v111, 0x3e000000, v48
	v_readlane_b32 s43, v255, 41
	s_and_saveexec_b64 s[76:77], s[42:43]
	s_xor_b64 s[76:77], exec, s[76:77]
	s_cbranch_execz .LBB0_875
	v_readlane_b32 s42, v255, 42
	v_readlane_b32 s43, v255, 43
	s_and_saveexec_b64 s[82:83], s[42:43]
	s_xor_b64 s[82:83], exec, s[82:83]
	v_mov_b32_e32 v48, v49
	v_mov_b32_e32 v49, v50
	s_mov_b32 s42, 0x3e000000
	v_pk_mul_f32 v[62:63], v[48:49], s[42:43] op_sel_hi:[1,0]
	v_mul_f32_e32 v112, 0x3e000000, v51
	v_max3_f32 v48, v110, v111, v62
	v_max3_f32 v110, v48, v63, v112
	s_andn2_saveexec_b64 s[82:83], s[82:83]
	v_mul_f32_e32 v48, 0x3e000000, v49
	v_mul_f32_e32 v49, 0x3e000000, v50
	v_cndmask_b32_e64 v111, v111, v151, s[14:15]
	v_cndmask_b32_e64 v62, v151, v48, s[16:17]
	v_cndmask_b32_e64 v63, v49, v151, s[18:19]
	v_mul_f32_e32 v49, 0x3e000000, v51
	v_max3_f32 v48, v110, v111, v62
	v_cndmask_b32_e64 v112, v49, v151, s[20:21]
	v_max3_f32 v110, v48, v63, v112
	s_or_b64 exec, exec, s[82:83]

.LBB0_878:
	s_or_b64 exec, exec, vcc
	s_nop 2
	s_and_b64 s[76:77], s[48:49], s[2:3]
	s_nor_b64 s[76:77], s[46:47], s[76:77]
	v_mov_b32_e32 v113, 0xff800000
	s_waitcnt lgkmcnt(1)
	v_mfma_f32_16x16x32_bf16 v[48:51], v[182:185], v[44:47], 0
	s_waitcnt lgkmcnt(0)
	v_mfma_f32_16x16x32_bf16 v[48:51], v[186:189], v[40:43], v[48:51]
	ds_read_b128 v[190:193], v101
	ds_read_b128 v[194:197], v101 offset:64
	v_mov_b32_e32 v64, 0xff800000
	v_mov_b32_e32 v65, 0xff800000
	s_and_saveexec_b64 vcc, s[76:77]
	s_cbranch_execz .LBB0_888
	s_nop 3
	v_mul_f32_e32 v109, 0x3e000000, v48
	s_and_saveexec_b64 s[76:77], s[50:51]
	s_xor_b64 s[76:77], exec, s[76:77]
	s_cbranch_execz .LBB0_885
	v_readlane_b32 s42, v255, 44
	v_readlane_b32 s43, v255, 45
	s_and_saveexec_b64 s[82:83], s[42:43]
	s_xor_b64 s[82:83], exec, s[82:83]
	v_mov_b32_e32 v48, v49
	v_mov_b32_e32 v49, v50
	s_mov_b32 s42, 0x3e000000
	v_pk_mul_f32 v[64:65], v[48:49], s[42:43] op_sel_hi:[1,0]
	v_mul_f32_e32 v113, 0x3e000000, v51
	v_max3_f32 v48, v110, v109, v64
	v_max3_f32 v110, v48, v65, v113
	s_andn2_saveexec_b64 s[82:83], s[82:83]
	v_mul_f32_e32 v48, 0x3e000000, v49
	v_mul_f32_e32 v49, 0x3e000000, v50
	v_cndmask_b32_e64 v109, v109, v151, s[14:15]
	v_cndmask_b32_e64 v64, v151, v48, s[16:17]
	v_cndmask_b32_e64 v65, v49, v151, s[18:19]
	v_mul_f32_e32 v49, 0x3e000000, v51
	v_max3_f32 v48, v110, v109, v64
	v_cndmask_b32_e64 v113, v49, v151, s[20:21]
	v_max3_f32 v110, v48, v65, v113
	s_or_b64 exec, exec, s[82:83]

.LBB0_888:
	s_or_b64 exec, exec, vcc
	s_nop 2
	s_and_b64 s[76:77], s[56:57], s[2:3]
	s_nor_b64 s[76:77], s[54:55], s[76:77]
	v_mov_b32_e32 v114, 0xff800000
	s_waitcnt lgkmcnt(1)
	v_mfma_f32_16x16x32_bf16 v[48:51], v[190:193], v[44:47], 0
	v_mov_b32_e32 v115, 0xff800000
	v_mov_b32_e32 v116, 0xff800000
	s_waitcnt lgkmcnt(0)
	v_mfma_f32_16x16x32_bf16 v[48:51], v[194:197], v[40:43], v[48:51]
	ds_read_b128 v[182:185], v102
	ds_read_b128 v[186:189], v102 offset:64
	v_mov_b32_e32 v66, 0xff800000
	v_mov_b32_e32 v67, 0xff800000
	s_and_saveexec_b64 vcc, s[76:77]
	s_cbranch_execz .LBB0_898
	s_nop 3
	v_mul_f32_e32 v115, 0x3e000000, v48
	s_and_saveexec_b64 s[76:77], s[58:59]
	s_xor_b64 s[76:77], exec, s[76:77]
	s_cbranch_execz .LBB0_895
	v_readlane_b32 s42, v255, 46
	v_readlane_b32 s43, v255, 47
	s_and_saveexec_b64 s[82:83], s[42:43]
	s_xor_b64 s[82:83], exec, s[82:83]
	v_mov_b32_e32 v48, v49
	v_mov_b32_e32 v49, v50
	s_mov_b32 s42, 0x3e000000
	v_pk_mul_f32 v[66:67], v[48:49], s[42:43] op_sel_hi:[1,0]
	v_mul_f32_e32 v116, 0x3e000000, v51
	v_max3_f32 v48, v110, v115, v66
	v_max3_f32 v110, v48, v67, v116
	s_andn2_saveexec_b64 s[82:83], s[82:83]
	v_mul_f32_e32 v48, 0x3e000000, v49
	v_mul_f32_e32 v49, 0x3e000000, v50
	v_cndmask_b32_e64 v115, v115, v151, s[14:15]
	v_cndmask_b32_e64 v66, v151, v48, s[16:17]
	v_cndmask_b32_e64 v67, v49, v151, s[18:19]
	v_mul_f32_e32 v49, 0x3e000000, v51
	v_max3_f32 v48, v110, v115, v66
	v_cndmask_b32_e64 v116, v49, v151, s[20:21]
	v_max3_f32 v110, v48, v67, v116
	s_or_b64 exec, exec, s[82:83]

.LBB0_898:
	s_or_b64 exec, exec, vcc
	s_nop 2
	s_and_b64 s[76:77], s[64:65], s[2:3]
	s_nor_b64 s[76:77], s[62:63], s[76:77]
	v_mov_b32_e32 v117, 0xff800000
	s_waitcnt lgkmcnt(1)
	v_mfma_f32_16x16x32_bf16 v[48:51], v[182:185], v[44:47], 0
	s_waitcnt lgkmcnt(0)
	v_mfma_f32_16x16x32_bf16 v[48:51], v[186:189], v[40:43], v[48:51]
	ds_read_b128 v[190:193], v103
	ds_read_b128 v[194:197], v103 offset:64
	v_mov_b32_e32 v68, 0xff800000
	v_mov_b32_e32 v69, 0xff800000
	s_and_saveexec_b64 vcc, s[76:77]
	s_cbranch_execz .LBB0_908
	s_nop 3
	v_mul_f32_e32 v114, 0x3e000000, v48
	s_and_saveexec_b64 s[76:77], s[66:67]
	s_xor_b64 s[76:77], exec, s[76:77]
	s_cbranch_execz .LBB0_905
	v_readlane_b32 s42, v255, 48
	v_readlane_b32 s43, v255, 49
	s_and_saveexec_b64 s[82:83], s[42:43]
	s_xor_b64 s[82:83], exec, s[82:83]
	v_mov_b32_e32 v48, v49
	v_mov_b32_e32 v49, v50
	s_mov_b32 s42, 0x3e000000
	v_pk_mul_f32 v[68:69], v[48:49], s[42:43] op_sel_hi:[1,0]
	v_mul_f32_e32 v117, 0x3e000000, v51
	v_max3_f32 v48, v110, v114, v68
	v_max3_f32 v110, v48, v69, v117
	s_andn2_saveexec_b64 s[82:83], s[82:83]
	v_mul_f32_e32 v48, 0x3e000000, v49
	v_mul_f32_e32 v49, 0x3e000000, v50
	v_cndmask_b32_e64 v114, v114, v151, s[14:15]
	v_cndmask_b32_e64 v68, v151, v48, s[16:17]
	v_cndmask_b32_e64 v69, v49, v151, s[18:19]
	v_mul_f32_e32 v49, 0x3e000000, v51
	v_max3_f32 v48, v110, v114, v68
	v_cndmask_b32_e64 v117, v49, v151, s[20:21]
	v_max3_f32 v110, v48, v69, v117
	s_or_b64 exec, exec, s[82:83]

.LBB0_908:
	s_or_b64 exec, exec, vcc
	s_nop 2
	s_and_b64 vcc, s[72:73], s[2:3]
	s_nor_b64 s[82:83], s[70:71], vcc
	v_mov_b32_e32 v118, 0xff800000
	s_waitcnt lgkmcnt(1)
	v_mfma_f32_16x16x32_bf16 v[48:51], v[190:193], v[44:47], 0
	v_mov_b32_e32 v119, 0xff800000
	v_mov_b32_e32 v120, 0xff800000
	s_waitcnt lgkmcnt(0)
	v_mfma_f32_16x16x32_bf16 v[48:51], v[194:197], v[40:43], v[48:51]
	ds_read_b128 v[182:185], v104
	ds_read_b128 v[186:189], v104 offset:64
	v_mov_b32_e32 v70, 0xff800000
	v_mov_b32_e32 v71, 0xff800000
	s_and_saveexec_b64 s[76:77], s[82:83]
	s_cbranch_execz .LBB0_918
	s_nop 3
	v_mul_f32_e32 v119, 0x3e000000, v48
	s_and_saveexec_b64 s[82:83], s[74:75]
	s_xor_b64 s[82:83], exec, s[82:83]
	s_cbranch_execz .LBB0_915
	s_mov_b64 s[90:91], exec
	v_readlane_b32 s42, v255, 50
	v_readlane_b32 s43, v255, 51
	s_and_b64 s[42:43], s[90:91], s[42:43]
	s_xor_b64 s[90:91], s[42:43], s[90:91]
	s_mov_b64 exec, s[42:43]
	v_mov_b32_e32 v48, v49
	v_mov_b32_e32 v49, v50
	s_mov_b32 s42, 0x3e000000
	v_pk_mul_f32 v[70:71], v[48:49], s[42:43] op_sel_hi:[1,0]
	v_mul_f32_e32 v120, 0x3e000000, v51
	v_max3_f32 v48, v110, v119, v70
	v_max3_f32 v110, v48, v71, v120
	s_andn2_saveexec_b64 s[90:91], s[90:91]
	v_mul_f32_e32 v48, 0x3e000000, v49
	v_mul_f32_e32 v49, 0x3e000000, v50
	v_cndmask_b32_e64 v119, v119, v151, s[14:15]
	v_cndmask_b32_e64 v70, v151, v48, s[16:17]
	v_cndmask_b32_e64 v71, v49, v151, s[18:19]
	v_mul_f32_e32 v49, 0x3e000000, v51
	v_max3_f32 v48, v110, v119, v70
	v_cndmask_b32_e64 v120, v49, v151, s[20:21]
	v_max3_f32 v110, v48, v71, v120
	s_or_b64 exec, exec, s[90:91]

.LBB0_918:
	s_or_b64 exec, exec, s[76:77]
	s_nop 2
	s_nor_b64 s[42:43], s[78:79], vcc
	v_mov_b32_e32 v121, 0xff800000
	s_waitcnt lgkmcnt(1)
	v_mfma_f32_16x16x32_bf16 v[48:51], v[182:185], v[44:47], 0
	s_waitcnt lgkmcnt(0)
	v_mfma_f32_16x16x32_bf16 v[48:51], v[186:189], v[40:43], v[48:51]
	ds_read_b128 v[190:193], v105
	ds_read_b128 v[194:197], v105 offset:64
	v_mov_b32_e32 v72, 0xff800000
	v_mov_b32_e32 v73, 0xff800000
	s_and_saveexec_b64 s[76:77], s[42:43]
	s_cbranch_execz .LBB0_928
	s_nop 3
	v_mul_f32_e32 v118, 0x3e000000, v48
	s_and_saveexec_b64 s[42:43], s[80:81]
	s_xor_b64 s[82:83], exec, s[42:43]
	s_cbranch_execz .LBB0_925
	v_readlane_b32 s90, v255, 52
	v_readlane_b32 s91, v255, 53
	s_and_saveexec_b64 s[42:43], s[90:91]
	s_xor_b64 s[90:91], exec, s[42:43]
	v_mov_b32_e32 v48, v49
	v_mov_b32_e32 v49, v50
	s_mov_b32 s42, 0x3e000000
	v_pk_mul_f32 v[72:73], v[48:49], s[42:43] op_sel_hi:[1,0]
	v_mul_f32_e32 v121, 0x3e000000, v51
	v_max3_f32 v48, v110, v118, v72
	v_max3_f32 v110, v48, v73, v121
	s_andn2_saveexec_b64 s[90:91], s[90:91]
	v_mul_f32_e32 v48, 0x3e000000, v49
	v_mul_f32_e32 v49, 0x3e000000, v50
	v_cndmask_b32_e64 v118, v118, v151, s[14:15]
	v_cndmask_b32_e64 v72, v151, v48, s[16:17]
	v_cndmask_b32_e64 v73, v49, v151, s[18:19]
	v_mul_f32_e32 v49, 0x3e000000, v51
	v_max3_f32 v48, v110, v118, v72
	v_cndmask_b32_e64 v121, v49, v151, s[20:21]
	v_max3_f32 v110, v48, v73, v121
	s_or_b64 exec, exec, s[90:91]

.LBB0_928:
	s_or_b64 exec, exec, s[76:77]
	s_nop 2
	s_and_b64 s[42:43], s[86:87], s[2:3]
	s_nor_b64 s[42:43], s[84:85], s[42:43]
	v_mov_b32_e32 v74, 0xff800000
	s_waitcnt lgkmcnt(1)
	v_mfma_f32_16x16x32_bf16 v[48:51], v[190:193], v[44:47], 0
	v_mov_b32_e32 v75, 0xff800000
	s_waitcnt lgkmcnt(0)
	v_mfma_f32_16x16x32_bf16 v[48:51], v[194:197], v[40:43], v[48:51]
	ds_read_b128 v[182:185], v106
	ds_read_b128 v[186:189], v106 offset:64
	v_mov_b32_e32 v122, 0xff800000
	v_mov_b32_e32 v123, 0xff800000
	v_mov_b32_e32 v124, 0xff800000
	s_and_saveexec_b64 s[76:77], s[42:43]
	s_cbranch_execz .LBB0_938
	s_nop 2
	v_mul_f32_e32 v123, 0x3e000000, v48
	s_and_saveexec_b64 s[42:43], s[88:89]
	s_xor_b64 s[82:83], exec, s[42:43]
	s_cbranch_execz .LBB0_935
	v_readlane_b32 s90, v255, 54
	v_readlane_b32 s91, v255, 55
	s_and_saveexec_b64 s[42:43], s[90:91]
	s_xor_b64 s[90:91], exec, s[42:43]
	v_mov_b32_e32 v48, v49
	v_mov_b32_e32 v49, v50
	s_mov_b32 s42, 0x3e000000
	v_pk_mul_f32 v[74:75], v[48:49], s[42:43] op_sel_hi:[1,0]
	v_mul_f32_e32 v124, 0x3e000000, v51
	v_max3_f32 v48, v110, v123, v74
	v_max3_f32 v110, v48, v75, v124
	s_andn2_saveexec_b64 s[90:91], s[90:91]
	v_mul_f32_e32 v48, 0x3e000000, v49
	v_mul_f32_e32 v49, 0x3e000000, v50
	v_cndmask_b32_e64 v123, v123, v151, s[14:15]
	v_cndmask_b32_e64 v74, v151, v48, s[16:17]
	v_cndmask_b32_e64 v75, v49, v151, s[18:19]
	v_mul_f32_e32 v49, 0x3e000000, v51
	v_max3_f32 v48, v110, v123, v74
	v_cndmask_b32_e64 v124, v49, v151, s[20:21]
	v_max3_f32 v110, v48, v75, v124
	s_or_b64 exec, exec, s[90:91]

.LBB0_938:
	s_or_b64 exec, exec, s[76:77]
	s_nop 1
	s_and_b64 s[2:3], s[94:95], s[2:3]
	s_nor_b64 s[42:43], s[92:93], s[2:3]
	s_waitcnt lgkmcnt(0)
	v_mfma_f32_16x16x32_bf16 v[44:47], v[182:185], v[44:47], 0
	s_waitcnt lgkmcnt(0)
	v_mfma_f32_16x16x32_bf16 v[40:43], v[186:189], v[40:43], v[44:47]
	s_nop 4
	v_mov_b32_e32 v44, 0xff800000
	v_mov_b32_e32 v45, 0xff800000
	v_mov_b32_e32 v46, 0xff800000
	s_and_saveexec_b64 s[2:3], s[42:43]
	s_cbranch_execz .LBB0_948
	v_mul_f32_e32 v122, 0x3e000000, v40
	s_and_saveexec_b64 s[42:43], s[96:97]
	s_xor_b64 s[76:77], exec, s[42:43]
	s_cbranch_execz .LBB0_945
	v_readlane_b32 s82, v255, 56
	v_readlane_b32 s83, v255, 57
	s_and_saveexec_b64 s[42:43], s[82:83]
	s_xor_b64 s[82:83], exec, s[42:43]
	v_mov_b32_e32 v40, v41
	v_mov_b32_e32 v41, v42
	s_mov_b32 s42, 0x3e000000
	v_pk_mul_f32 v[44:45], v[40:41], s[42:43] op_sel_hi:[1,0]
	v_mul_f32_e32 v46, 0x3e000000, v43
	v_max3_f32 v40, v110, v122, v44
	v_max3_f32 v110, v40, v45, v46
	s_andn2_saveexec_b64 s[82:83], s[82:83]
	v_mul_f32_e32 v40, 0x3e000000, v41
	v_mul_f32_e32 v41, 0x3e000000, v42
	v_cndmask_b32_e64 v122, v122, v151, s[14:15]
	v_cndmask_b32_e64 v44, v151, v40, s[16:17]
	v_cndmask_b32_e64 v45, v41, v151, s[18:19]
	v_mul_f32_e32 v41, 0x3e000000, v43
	v_max3_f32 v40, v110, v122, v44
	v_cndmask_b32_e64 v46, v41, v151, s[20:21]
	v_max3_f32 v110, v40, v45, v46
	s_or_b64 exec, exec, s[82:83]

.LBB0_948:
	s_or_b64 exec, exec, s[2:3]
	ds_bpermute_b32 v40, v81, v110
	v_max_f32_e32 v41, v110, v110
	s_lshl_b32 s2, -1, s36
	s_andn2_b32 s82, s61, s2
	s_waitcnt lgkmcnt(0)
	v_max_f32_e32 v40, v40, v40
	v_max_f32_e32 v40, v41, v40
	ds_bpermute_b32 v41, v82, v40
	s_waitcnt lgkmcnt(0)
	ds_read_b64_tr_b16 v[198:199], v84
	ds_read_b64_tr_b16 v[202:203], v84 offset:32
	ds_read_b64_tr_b16 v[206:207], v84 offset:64
	ds_read_b64_tr_b16 v[210:211], v84 offset:96
	ds_read_b64_tr_b16 v[200:201], v84 offset:2304
	ds_read_b64_tr_b16 v[204:205], v84 offset:2336
	ds_read_b64_tr_b16 v[208:209], v84 offset:2368
	ds_read_b64_tr_b16 v[212:213], v84 offset:2400
	v_max_f32_e32 v41, v41, v41
	v_max_f32_e32 v110, v40, v41
	v_sub_f32_e32 v41, v52, v110
	v_sub_f32_e32 v52, v111, v110
	v_mul_f32_e32 v52, 0x3fb8aa3b, v52
	v_sub_f32_e32 v40, v107, v110
	v_exp_f32_e32 v107, v52
	v_sub_f32_e32 v52, v62, v110
	v_mul_f32_e32 v52, 0x3fb8aa3b, v52
	v_sub_f32_e32 v51, v108, v110
	v_exp_f32_e32 v108, v52
	v_sub_f32_e32 v52, v63, v110
	v_mul_f32_e32 v52, 0x3fb8aa3b, v52
	v_exp_f32_e32 v111, v52
	v_sub_f32_e32 v52, v112, v110
	v_mul_f32_e32 v52, 0x3fb8aa3b, v52
	v_exp_f32_e32 v112, v52
	v_sub_f32_e32 v52, v109, v110
	v_mul_f32_e32 v52, 0x3fb8aa3b, v52
	v_exp_f32_e32 v109, v52
	v_sub_f32_e32 v52, v64, v110
	v_mul_f32_e32 v40, 0x3fb8aa3b, v40
	v_mul_f32_e32 v52, 0x3fb8aa3b, v52
	v_exp_f32_e32 v40, v40
	v_mul_f32_e32 v41, 0x3fb8aa3b, v41
	v_exp_f32_e32 v125, v52
	v_sub_f32_e32 v52, v65, v110
	v_exp_f32_e32 v41, v41
	v_mul_f32_e32 v52, 0x3fb8aa3b, v52
	v_exp_f32_e32 v126, v52
	v_sub_f32_e32 v52, v113, v110
	v_mul_f32_e32 v52, 0x3fb8aa3b, v52
	v_add_f32_e32 v42, 0, v40
	v_exp_f32_e32 v113, v52
	v_sub_f32_e32 v52, v115, v110
	v_add_f32_e32 v43, v41, v42
	v_sub_f32_e32 v42, v53, v110
	v_mul_f32_e32 v52, 0x3fb8aa3b, v52
	v_mul_f32_e32 v42, 0x3fb8aa3b, v42
	v_exp_f32_e32 v127, v52
	v_sub_f32_e32 v52, v66, v110
	v_exp_f32_e32 v42, v42
	v_mul_f32_e32 v52, 0x3fb8aa3b, v52
	v_exp_f32_e32 v128, v52
	v_sub_f32_e32 v52, v67, v110
	v_mul_f32_e32 v52, 0x3fb8aa3b, v52
	v_exp_f32_e32 v134, v52
	v_sub_f32_e32 v52, v116, v110
	v_add_f32_e32 v47, v42, v43
	v_sub_f32_e32 v43, v61, v110
	v_mul_f32_e32 v52, 0x3fb8aa3b, v52
	v_mul_f32_e32 v43, 0x3fb8aa3b, v43
	v_sub_f32_e32 v48, v59, v110
	v_exp_f32_e32 v135, v52
	v_sub_f32_e32 v52, v114, v110
	v_exp_f32_e32 v43, v43
	v_mul_f32_e32 v48, 0x3fb8aa3b, v48
	v_sub_f32_e32 v49, v54, v110
	v_mul_f32_e32 v52, 0x3fb8aa3b, v52
	v_exp_f32_e32 v48, v48
	v_mul_f32_e32 v49, 0x3fb8aa3b, v49
	v_sub_f32_e32 v50, v55, v110
	v_exp_f32_e32 v136, v52
	v_sub_f32_e32 v52, v68, v110
	v_exp_f32_e32 v49, v49
	v_mul_f32_e32 v50, 0x3fb8aa3b, v50
	v_mul_f32_e32 v52, 0x3fb8aa3b, v52
	v_exp_f32_e32 v50, v50
	v_mul_f32_e32 v51, 0x3fb8aa3b, v51
	v_exp_f32_e32 v137, v52
	v_sub_f32_e32 v52, v69, v110
	v_add_f32_e32 v47, v43, v47
	v_exp_f32_e32 v51, v51
	v_mul_f32_e32 v52, 0x3fb8aa3b, v52
	v_add_f32_e32 v47, v48, v47
	v_exp_f32_e32 v138, v52
	v_sub_f32_e32 v52, v117, v110
	v_add_f32_e32 v47, v49, v47
	v_mul_f32_e32 v52, 0x3fb8aa3b, v52
	v_add_f32_e32 v47, v50, v47
	v_exp_f32_e32 v139, v52
	v_sub_f32_e32 v52, v119, v110
	v_add_f32_e32 v47, v51, v47
	v_mul_f32_e32 v52, 0x3fb8aa3b, v52
	v_add_f32_e32 v47, v107, v47
	v_exp_f32_e32 v140, v52
	v_sub_f32_e32 v52, v70, v110
	v_add_f32_e32 v47, v108, v47
	v_mul_f32_e32 v52, 0x3fb8aa3b, v52
	v_add_f32_e32 v47, v111, v47
	v_exp_f32_e32 v141, v52
	v_sub_f32_e32 v52, v71, v110
	v_add_f32_e32 v47, v112, v47
	v_mul_f32_e32 v52, 0x3fb8aa3b, v52
	v_add_f32_e32 v47, v109, v47
	v_exp_f32_e32 v142, v52
	v_sub_f32_e32 v52, v120, v110
	v_add_f32_e32 v47, v125, v47
	v_mul_f32_e32 v52, 0x3fb8aa3b, v52
	v_add_f32_e32 v47, v126, v47
	v_exp_f32_e32 v120, v52
	v_sub_f32_e32 v52, v118, v110
	v_add_f32_e32 v47, v113, v47
	v_mul_f32_e32 v52, 0x3fb8aa3b, v52
	v_add_f32_e32 v47, v127, v47
	v_exp_f32_e32 v143, v52
	v_sub_f32_e32 v52, v72, v110
	v_add_f32_e32 v47, v128, v47
	v_mul_f32_e32 v52, 0x3fb8aa3b, v52
	v_add_f32_e32 v47, v134, v47
	v_exp_f32_e32 v144, v52
	v_sub_f32_e32 v52, v73, v110
	v_add_f32_e32 v47, v135, v47
	v_mul_f32_e32 v52, 0x3fb8aa3b, v52
	v_add_f32_e32 v47, v136, v47
	v_exp_f32_e32 v145, v52
	v_sub_f32_e32 v52, v121, v110
	v_add_f32_e32 v47, v137, v47
	v_mul_f32_e32 v52, 0x3fb8aa3b, v52
	v_add_f32_e32 v47, v138, v47
	v_exp_f32_e32 v121, v52
	v_sub_f32_e32 v52, v123, v110
	v_add_f32_e32 v47, v139, v47
	v_mul_f32_e32 v52, 0x3fb8aa3b, v52
	v_add_f32_e32 v47, v140, v47
	v_exp_f32_e32 v123, v52
	v_sub_f32_e32 v52, v74, v110
	v_add_f32_e32 v47, v141, v47
	v_mul_f32_e32 v52, 0x3fb8aa3b, v52
	v_add_f32_e32 v47, v142, v47
	v_exp_f32_e32 v74, v52
	v_sub_f32_e32 v52, v75, v110
	v_add_f32_e32 v47, v120, v47
	v_mul_f32_e32 v52, 0x3fb8aa3b, v52
	v_add_f32_e32 v47, v143, v47
	v_exp_f32_e32 v75, v52
	v_sub_f32_e32 v52, v124, v110
	v_add_f32_e32 v47, v144, v47
	v_mul_f32_e32 v52, 0x3fb8aa3b, v52
	v_add_f32_e32 v47, v145, v47
	v_exp_f32_e32 v124, v52
	v_sub_f32_e32 v52, v122, v110
	v_add_f32_e32 v47, v121, v47
	v_mul_f32_e32 v52, 0x3fb8aa3b, v52
	v_sub_f32_e32 v44, v44, v110
	v_sub_f32_e32 v45, v45, v110
	v_add_f32_e32 v47, v123, v47
	v_exp_f32_e32 v122, v52
	v_mul_f32_e32 v44, 0x3fb8aa3b, v44
	v_mul_f32_e32 v45, 0x3fb8aa3b, v45
	v_add_f32_e32 v47, v74, v47
	v_exp_f32_e32 v153, v44
	v_exp_f32_e32 v154, v45
	v_sub_f32_e32 v45, v46, v110
	v_add_f32_e32 v47, v75, v47
	v_mul_f32_e32 v45, 0x3fb8aa3b, v45
	v_add_f32_e32 v47, v124, v47
	v_exp_f32_e32 v155, v45
	v_add_f32_e32 v47, v122, v47
	v_add_f32_e32 v44, v153, v47
	v_add_f32_e32 v44, v154, v44
	v_add_f32_e32 v44, v155, v44
	ds_bpermute_b32 v45, v81, v44
	v_cvt_pk_bf16_f32 v40, v40, v41
	v_cvt_pk_bf16_f32 v41, v42, v43
	v_cvt_pk_bf16_f32 v42, v48, v49
	v_cvt_pk_bf16_f32 v43, v50, v51
	s_waitcnt lgkmcnt(0)
	v_add_f32_e32 v59, v44, v45
	s_waitcnt lgkmcnt(0)
	ds_bpermute_b32 v61, v82, v59
	v_mfma_f32_16x16x32_bf16 v[62:65], v[40:43], v[198:201], 0
	v_mfma_f32_16x16x32_bf16 v[52:55], v[40:43], v[202:205], 0
	v_mfma_f32_16x16x32_bf16 v[48:51], v[40:43], v[206:209], 0
	v_mfma_f32_16x16x32_bf16 v[40:43], v[40:43], v[210:213], 0
	v_cvt_pk_bf16_f32 v44, v107, v108
	v_cvt_pk_bf16_f32 v45, v111, v112
	v_cvt_pk_bf16_f32 v46, v109, v125
	v_cvt_pk_bf16_f32 v47, v126, v113
	ds_read_b64_tr_b16 v[116:117], v85
	ds_read_b64_tr_b16 v[112:113], v85 offset:32
	ds_read_b64_tr_b16 v[70:71], v85 offset:64
	ds_read_b64_tr_b16 v[66:67], v85 offset:96
	ds_read_b64_tr_b16 v[118:119], v85 offset:2304
	ds_read_b64_tr_b16 v[114:115], v85 offset:2336
	ds_read_b64_tr_b16 v[72:73], v85 offset:2368
	ds_read_b64_tr_b16 v[68:69], v85 offset:2400
	s_waitcnt lgkmcnt(0)
	s_nop 0
	v_mfma_f32_16x16x32_bf16 v[62:65], v[44:47], v[116:119], v[62:65]
	v_mfma_f32_16x16x32_bf16 v[52:55], v[44:47], v[112:115], v[52:55]
	v_mfma_f32_16x16x32_bf16 v[48:51], v[44:47], v[70:73], v[48:51]
	v_mfma_f32_16x16x32_bf16 v[40:43], v[44:47], v[66:69], v[40:43]
	v_cvt_pk_bf16_f32 v44, v127, v128
	v_cvt_pk_bf16_f32 v45, v134, v135
	v_cvt_pk_bf16_f32 v46, v136, v137
	v_cvt_pk_bf16_f32 v47, v138, v139
	ds_read_b64_tr_b16 v[116:117], v86
	ds_read_b64_tr_b16 v[112:113], v86 offset:32
	ds_read_b64_tr_b16 v[70:71], v86 offset:64
	ds_read_b64_tr_b16 v[66:67], v86 offset:96
	ds_read_b64_tr_b16 v[118:119], v86 offset:2304
	ds_read_b64_tr_b16 v[114:115], v86 offset:2336
	ds_read_b64_tr_b16 v[72:73], v86 offset:2368
	ds_read_b64_tr_b16 v[68:69], v86 offset:2400
	s_waitcnt lgkmcnt(0)
	s_nop 0
	v_mfma_f32_16x16x32_bf16 v[62:65], v[44:47], v[116:119], v[62:65]
	v_mfma_f32_16x16x32_bf16 v[52:55], v[44:47], v[112:115], v[52:55]
	v_mfma_f32_16x16x32_bf16 v[48:51], v[44:47], v[70:73], v[48:51]
	v_mfma_f32_16x16x32_bf16 v[40:43], v[44:47], v[66:69], v[40:43]
	v_cvt_pk_bf16_f32 v44, v140, v141
	v_cvt_pk_bf16_f32 v45, v142, v120
	v_cvt_pk_bf16_f32 v46, v143, v144
	v_cvt_pk_bf16_f32 v47, v145, v121
	ds_read_b64_tr_b16 v[116:117], v87
	ds_read_b64_tr_b16 v[112:113], v87 offset:32
	ds_read_b64_tr_b16 v[70:71], v87 offset:64
	ds_read_b64_tr_b16 v[66:67], v87 offset:96
	ds_read_b64_tr_b16 v[118:119], v87 offset:2304
	ds_read_b64_tr_b16 v[114:115], v87 offset:2336
	ds_read_b64_tr_b16 v[72:73], v87 offset:2368
	ds_read_b64_tr_b16 v[68:69], v87 offset:2400
	s_waitcnt lgkmcnt(0)
	s_nop 0
	v_mfma_f32_16x16x32_bf16 v[62:65], v[44:47], v[116:119], v[62:65]
	v_mfma_f32_16x16x32_bf16 v[52:55], v[44:47], v[112:115], v[52:55]
	v_mfma_f32_16x16x32_bf16 v[48:51], v[44:47], v[70:73], v[48:51]
	v_cvt_pk_bf16_f32 v70, v123, v74
	v_cvt_pk_bf16_f32 v71, v75, v124
	v_cvt_pk_bf16_f32 v72, v122, v153
	v_mfma_f32_16x16x32_bf16 v[66:69], v[44:47], v[66:69], v[40:43]
	v_cvt_pk_bf16_f32 v73, v154, v155
	ds_read_b64_tr_b16 v[40:41], v88
	ds_read_b64_tr_b16 v[44:45], v88 offset:32
	ds_read_b64_tr_b16 v[116:117], v88 offset:64
	ds_read_b64_tr_b16 v[112:113], v88 offset:96
	ds_read_b64_tr_b16 v[42:43], v88 offset:2304
	ds_read_b64_tr_b16 v[46:47], v88 offset:2336
	ds_read_b64_tr_b16 v[118:119], v88 offset:2368
	ds_read_b64_tr_b16 v[114:115], v88 offset:2400
	s_waitcnt lgkmcnt(0)
	s_nop 2
	v_mfma_f32_16x16x32_bf16 v[40:43], v[70:73], v[40:43], v[62:65]
	v_mfma_f32_16x16x32_bf16 v[44:47], v[70:73], v[44:47], v[52:55]
	s_nop 1
	v_mov_b64_e32 v[62:63], s[36:37]
	v_mfma_f32_16x16x32_bf16 v[48:51], v[70:73], v[116:119], v[48:51]
	v_mfma_f32_16x16x32_bf16 v[52:55], v[70:73], v[112:115], v[66:69]
	s_and_saveexec_b64 s[42:43], s[4:5]
	s_xor_b64 s[76:77], exec, s[42:43]
	s_ashr_i32 s69, s68, 31
	s_ashr_i32 s61, s60, 31
	s_lshl_b64 s[2:3], s[68:69], 14
	s_lshl_b64 s[42:43], s[60:61], 12
	s_add_u32 s2, s2, s42
	s_addc_u32 s3, s3, s43
	s_or_b32 s2, s2, s82
	v_mov_b64_e32 v[62:63], s[36:37]
	s_or_saveexec_b64 s[76:77], s[76:77]
	s_bfe_u32 s11, s98, 0x30005
	s_waitcnt lgkmcnt(0)
	v_add_f32_e32 v59, v59, v61
	s_lshl_b32 s35, s35, 7
	v_mov_b64_e32 v[64:65], s[2:3]
	s_xor_b64 exec, exec, s[76:77]
	s_cbranch_execz .LBB0_845
	s_mov_b32 s2, 0x800000
	v_cmp_gt_f32_e64 s[2:3], s2, v59
	v_add_u32_e32 v64, s35, v80
	v_ashrrev_i32_e32 v65, 31, v64
	v_cndmask_b32_e64 v61, 0, 32, s[2:3]
	v_ldexp_f32 v61, v59, v61
	v_log_f32_e32 v61, v61
	v_lshlrev_b64 v[64:65], s36, v[64:65]
	s_mov_b32 s36, 0x3f317217
	s_ashr_i32 s69, s68, 31
	v_mul_f32_e32 v63, 0x3f317217, v61
	v_fma_f32 v63, v61, s36, -v63
	v_fmac_f32_e32 v63, 0x3377d1cf, v61
	s_mov_b32 s36, 0x7f800000
	v_fmac_f32_e32 v63, 0x3f317217, v61
	v_cmp_lt_f32_e64 vcc, |v61|, s36
	s_ashr_i32 s61, s60, 31
	s_lshl_b64 s[42:43], s[60:61], 12
	v_cndmask_b32_e32 v61, v61, v63, vcc
	v_cndmask_b32_e64 v63, 0, v152, s[2:3]
	s_lshl_b64 s[2:3], s[68:69], 14
	s_add_u32 s2, s2, s42
	s_addc_u32 s3, s3, s43
	s_or_b32 s2, s2, s82
	v_lshl_add_u64 v[64:65], v[64:65], 0, s[2:3]
	v_lshlrev_b64 v[64:65], 5, v[64:65]
	v_sub_f32_e32 v61, v61, v63
	v_lshl_add_u64 v[64:65], s[0:1], 0, v[64:65]
	s_lshl_b32 s36, s11, 2
	v_add_f32_e32 v61, v110, v61
	v_lshl_add_u64 v[64:65], v[64:65], 0, s[36:37]
	global_store_dword v[64:65], v61, off
	v_mov_b64_e32 v[64:65], s[2:3]
	s_branch .LBB0_845
